# prologue x-prompt row sum-of-squares: wave_sum via DPP row ops + permlane swaps instead of 24 serialized ds_bpermute round trips per trip
# speedup vs baseline: 1.0032x; 1.0014x over previous
.LBB0_76:
	s_waitcnt lgkmcnt(0)
	v_add_co_u32_e32 v4, vcc, 0xffffd000, v58
	v_lshl_add_u64 v[60:61], s[30:31], 0, v[56:57]
	s_nop 0
	v_addc_co_u32_e32 v5, vcc, -1, v59, vcc
	global_load_dwordx4 v[78:81], v[4:5], off offset:-3072
	global_load_dwordx4 v[82:85], v[4:5], off offset:-2048
	global_load_dwordx4 v[86:89], v[4:5], off offset:-1024
	global_load_dwordx4 v[90:93], v[4:5], off
	global_load_dwordx4 v[18:21], v[58:59], off offset:-3072
	global_load_dwordx4 v[14:17], v[58:59], off offset:-2048
	global_load_dwordx4 v[10:13], v[58:59], off offset:-1024
	global_load_dwordx4 v[6:9], v[58:59], off
	v_add_co_u32_e32 v4, vcc, 0xffffe000, v58
	s_waitcnt vmcnt(6)
	v_mul_f32_e32 v62, v83, v83
	v_addc_co_u32_e32 v5, vcc, -1, v59, vcc
	v_add_co_u32_e32 v22, vcc, 0xfffff000, v58
	global_load_dwordx4 v[50:53], v[4:5], off offset:-3072
	global_load_dwordx4 v[46:49], v[4:5], off offset:-2048
	global_load_dwordx4 v[42:45], v[4:5], off offset:-1024
	global_load_dwordx4 v[38:41], v[4:5], off
	v_addc_co_u32_e32 v23, vcc, -1, v59, vcc
	global_load_dwordx4 v[34:37], v[22:23], off offset:-3072
	global_load_dwordx4 v[30:33], v[22:23], off offset:-2048
	global_load_dwordx4 v[26:29], v[22:23], off offset:-1024
	s_nop 0
	global_load_dwordx4 v[22:25], v[58:59], off offset:-4096
	v_cmp_lt_i32_e32 vcc, v66, v65
	v_mul_f32_e32 v5, v81, v81
	v_mul_f32_e32 v63, v85, v85
	v_cndmask_b32_e32 v2, v64, v66, vcc
	v_lshlrev_b32_e32 v72, 2, v2
	v_mul_f32_e32 v2, v79, v79
	s_waitcnt vmcnt(13)
	v_mul_f32_e32 v73, v87, v87
	v_mul_f32_e32 v74, v89, v89
	v_fmac_f32_e32 v2, v78, v78
	v_fmac_f32_e32 v5, v80, v80
	v_fmac_f32_e32 v62, v82, v82
	v_fmac_f32_e32 v63, v84, v84
	s_waitcnt vmcnt(12)
	v_mul_f32_e32 v75, v91, v91
	v_mul_f32_e32 v76, v93, v93
	v_fmac_f32_e32 v73, v86, v86
	v_fmac_f32_e32 v74, v88, v88
	v_add_f32_e32 v2, v2, v5
	v_add_f32_e32 v5, v62, v63
	v_fmac_f32_e32 v75, v90, v90
	v_fmac_f32_e32 v76, v92, v92
	v_add_f32_e32 v62, v73, v74
	v_add_f32_e32 v2, v2, v5
	v_add_f32_e32 v63, v75, v76
	v_add_f32_e32 v2, v2, v62
	v_add_f32_e32 v2, v2, v63
	v_cmp_lt_i32_e32 vcc, v67, v65
	s_nop 1
	v_add_f32_dpp v2, v2, v2 quad_perm:[1,0,3,2] row_mask:0xf bank_mask:0xf
	v_cndmask_b32_e32 v4, v64, v67, vcc
	v_lshlrev_b32_e32 v73, 2, v4
	v_cmp_lt_i32_e32 vcc, v68, v65
	s_nop 1
	v_add_f32_dpp v2, v2, v2 quad_perm:[2,3,0,1] row_mask:0xf bank_mask:0xf
	v_cndmask_b32_e32 v62, v64, v68, vcc
	v_lshlrev_b32_e32 v76, 2, v62
	v_cmp_lt_i32_e32 vcc, v69, v65
	v_cvt_pk_bf16_f32 v4, v78, v79
	s_nop 1
	v_add_f32_dpp v2, v2, v2 row_half_mirror row_mask:0xf bank_mask:0xf
	v_cndmask_b32_e32 v74, v64, v69, vcc
	v_lshlrev_b32_e32 v75, 2, v74
	v_cmp_lt_i32_e32 vcc, v70, v65
	s_nop 1
	v_add_f32_dpp v2, v2, v2 row_mirror row_mask:0xf bank_mask:0xf
	v_cndmask_b32_e32 v5, v64, v70, vcc
	v_lshlrev_b32_e32 v74, 2, v5
	v_cmp_lt_i32_e32 vcc, v71, v65
	v_cvt_pk_bf16_f32 v5, v80, v81
	v_mov_b32_e32 v78, v2
	v_mov_b32_e32 v100, v2
	s_nop 1
	v_permlane16_swap_b32 v78, v100
	v_add_f32_e32 v2, v78, v100
	v_cndmask_b32_e32 v77, v64, v71, vcc
	v_add_co_u32_e32 v62, vcc, s35, v60
	v_lshlrev_b32_e32 v77, 2, v77
	s_nop 0
	v_addc_co_u32_e32 v63, vcc, 0, v61, vcc
	global_store_dwordx2 v[62:63], v[4:5], off
	v_cvt_pk_bf16_f32 v4, v82, v83
	v_cvt_pk_bf16_f32 v5, v84, v85
	global_store_dwordx2 v[62:63], v[4:5], off offset:512
	v_cvt_pk_bf16_f32 v4, v86, v87
	v_cvt_pk_bf16_f32 v5, v88, v89
	global_store_dwordx2 v[62:63], v[4:5], off offset:1024
	v_mov_b32_e32 v4, v2
	v_mov_b32_e32 v100, v2
	s_nop 1
	v_permlane32_swap_b32 v100, v4
	v_cvt_pk_bf16_f32 v78, v90, v91
	v_cvt_pk_bf16_f32 v79, v92, v93
	global_store_dwordx2 v[62:63], v[78:79], off offset:1536
	v_lshl_add_u64 v[62:63], s[30:31], 0, v[54:55]
	s_and_saveexec_b64 s[42:43], s[6:7]
	s_cbranch_execz .LBB0_78
	v_add_f32_e32 v2, v2, v4
	v_add_co_u32_e32 v78, vcc, 0x10900000, v62
	v_cndmask_b32_e64 v2, 0, v2, s[4:5]
	s_nop 0
	v_addc_co_u32_e32 v79, vcc, 0, v63, vcc
	v_mov_b32_e32 v4, v3
	v_mov_b32_e32 v5, v3
	global_store_dwordx4 v[78:79], v[2:5], off
.LBB0_78:
	s_or_b64 exec, exec, s[42:43]
	s_waitcnt vmcnt(11)
	v_mul_f32_e32 v2, v51, v51
	s_waitcnt lgkmcnt(0)
	v_mul_f32_e32 v4, v53, v53
	v_fmac_f32_e32 v2, v50, v50
	v_fmac_f32_e32 v4, v52, v52
	v_add_f32_e32 v2, v2, v4
	s_waitcnt vmcnt(10)
	v_mul_f32_e32 v4, v47, v47
	v_mul_f32_e32 v5, v49, v49
	v_fmac_f32_e32 v4, v46, v46
	v_fmac_f32_e32 v5, v48, v48
	v_add_f32_e32 v4, v4, v5
	v_add_f32_e32 v2, v2, v4
	s_waitcnt vmcnt(9)
	v_mul_f32_e32 v4, v43, v43
	v_mul_f32_e32 v5, v45, v45
	v_fmac_f32_e32 v4, v42, v42
	v_fmac_f32_e32 v5, v44, v44
	v_add_f32_e32 v4, v4, v5
	v_add_f32_e32 v2, v2, v4
	s_waitcnt vmcnt(8)
	v_mul_f32_e32 v4, v39, v39
	v_mul_f32_e32 v5, v41, v41
	v_fmac_f32_e32 v4, v38, v38
	v_fmac_f32_e32 v5, v40, v40
	v_add_f32_e32 v4, v4, v5
	v_add_f32_e32 v2, v2, v4
	s_nop 1
	v_add_f32_dpp v2, v2, v2 quad_perm:[1,0,3,2] row_mask:0xf bank_mask:0xf
	s_nop 1
	v_add_f32_dpp v2, v2, v2 quad_perm:[2,3,0,1] row_mask:0xf bank_mask:0xf
	v_cvt_pk_bf16_f32 v4, v50, v51
	v_cvt_pk_bf16_f32 v5, v52, v53
	v_add_co_u32_e32 v50, vcc, 0x5900000, v60
	s_nop 1
	v_add_f32_dpp v2, v2, v2 row_half_mirror row_mask:0xf bank_mask:0xf
	v_addc_co_u32_e32 v51, vcc, 0, v61, vcc
	global_store_dwordx2 v[50:51], v[4:5], off offset:2048
	v_cvt_pk_bf16_f32 v4, v46, v47
	s_nop 1
	v_add_f32_dpp v2, v2, v2 row_mirror row_mask:0xf bank_mask:0xf
	v_cvt_pk_bf16_f32 v5, v48, v49
	global_store_dwordx2 v[50:51], v[4:5], off offset:2560
	v_cvt_pk_bf16_f32 v42, v42, v43
	v_cvt_pk_bf16_f32 v43, v44, v45
	v_mov_b32_e32 v46, v2
	v_mov_b32_e32 v100, v2
	s_nop 1
	v_permlane16_swap_b32 v46, v100
	v_add_f32_e32 v2, v46, v100
	v_mov_b32_e32 v4, v2
	v_mov_b32_e32 v100, v2
	s_nop 1
	v_permlane32_swap_b32 v100, v4
	global_store_dwordx2 v[50:51], v[42:43], off offset:3072
	v_cvt_pk_bf16_f32 v38, v38, v39
	v_cvt_pk_bf16_f32 v39, v40, v41
	global_store_dwordx2 v[50:51], v[38:39], off offset:3584
	s_and_saveexec_b64 s[42:43], s[6:7]
	s_cbranch_execz .LBB0_80
	v_add_f32_e32 v2, v2, v4
	v_add_co_u32_e32 v38, vcc, 0x10900000, v62
	v_cndmask_b32_e64 v2, 0, v2, s[4:5]
	s_nop 0
	v_addc_co_u32_e32 v39, vcc, 0, v63, vcc
	v_mov_b32_e32 v4, v3
	v_mov_b32_e32 v5, v3
	global_store_dwordx4 v[38:39], v[2:5], off offset:128
.LBB0_80:
	s_or_b64 exec, exec, s[42:43]
	s_waitcnt vmcnt(11)
	v_mul_f32_e32 v2, v35, v35
	s_waitcnt lgkmcnt(0)
	v_mul_f32_e32 v4, v37, v37
	v_fmac_f32_e32 v2, v34, v34
	v_fmac_f32_e32 v4, v36, v36
	v_add_f32_e32 v2, v2, v4
	s_waitcnt vmcnt(10)
	v_mul_f32_e32 v4, v31, v31
	v_mul_f32_e32 v5, v33, v33
	v_fmac_f32_e32 v4, v30, v30
	v_fmac_f32_e32 v5, v32, v32
	v_add_f32_e32 v4, v4, v5
	v_add_f32_e32 v2, v2, v4
	s_waitcnt vmcnt(9)
	v_mul_f32_e32 v4, v27, v27
	v_mul_f32_e32 v5, v29, v29
	v_fmac_f32_e32 v4, v26, v26
	v_fmac_f32_e32 v5, v28, v28
	v_add_f32_e32 v4, v4, v5
	v_add_f32_e32 v2, v2, v4
	s_waitcnt vmcnt(8)
	v_mul_f32_e32 v4, v23, v23
	v_mul_f32_e32 v5, v25, v25
	v_fmac_f32_e32 v4, v22, v22
	v_fmac_f32_e32 v5, v24, v24
	v_add_f32_e32 v4, v4, v5
	v_add_f32_e32 v2, v2, v4
	s_nop 1
	v_add_f32_dpp v2, v2, v2 quad_perm:[1,0,3,2] row_mask:0xf bank_mask:0xf
	s_nop 1
	v_add_f32_dpp v2, v2, v2 quad_perm:[2,3,0,1] row_mask:0xf bank_mask:0xf
	v_cvt_pk_bf16_f32 v4, v34, v35
	v_cvt_pk_bf16_f32 v5, v36, v37
	v_add_co_u32_e32 v34, vcc, 0x5901000, v60
	s_nop 1
	v_add_f32_dpp v2, v2, v2 row_half_mirror row_mask:0xf bank_mask:0xf
	v_addc_co_u32_e32 v35, vcc, 0, v61, vcc
	global_store_dwordx2 v[34:35], v[4:5], off
	v_cvt_pk_bf16_f32 v4, v30, v31
	s_nop 1
	v_add_f32_dpp v2, v2, v2 row_mirror row_mask:0xf bank_mask:0xf
	v_cvt_pk_bf16_f32 v5, v32, v33
	global_store_dwordx2 v[34:35], v[4:5], off offset:512
	v_cvt_pk_bf16_f32 v26, v26, v27
	v_cvt_pk_bf16_f32 v27, v28, v29
	v_mov_b32_e32 v30, v2
	v_mov_b32_e32 v100, v2
	s_nop 1
	v_permlane16_swap_b32 v30, v100
	v_add_f32_e32 v2, v30, v100
	v_mov_b32_e32 v4, v2
	v_mov_b32_e32 v100, v2
	s_nop 1
	v_permlane32_swap_b32 v100, v4
	global_store_dwordx2 v[34:35], v[26:27], off offset:1024
	v_cvt_pk_bf16_f32 v22, v22, v23
	v_cvt_pk_bf16_f32 v23, v24, v25
	global_store_dwordx2 v[34:35], v[22:23], off offset:1536
	s_and_saveexec_b64 s[42:43], s[6:7]
	s_cbranch_execz .LBB0_82
	v_add_f32_e32 v2, v2, v4
	v_add_co_u32_e32 v22, vcc, 0x10900000, v62
	v_cndmask_b32_e64 v2, 0, v2, s[4:5]
	s_nop 0
	v_addc_co_u32_e32 v23, vcc, 0, v63, vcc
	v_mov_b32_e32 v4, v3
	v_mov_b32_e32 v5, v3
	global_store_dwordx4 v[22:23], v[2:5], off offset:256
.LBB0_82:
	s_or_b64 exec, exec, s[42:43]
	s_nop 0
	v_mul_f32_e32 v2, v19, v19
	s_waitcnt lgkmcnt(0)
	v_mul_f32_e32 v4, v21, v21
	v_fmac_f32_e32 v2, v18, v18
	v_fmac_f32_e32 v4, v20, v20
	v_add_f32_e32 v2, v2, v4
	v_mul_f32_e32 v4, v15, v15
	v_mul_f32_e32 v5, v17, v17
	v_fmac_f32_e32 v4, v14, v14
	v_fmac_f32_e32 v5, v16, v16
	v_add_f32_e32 v4, v4, v5
	v_add_f32_e32 v2, v2, v4
	v_mul_f32_e32 v4, v11, v11
	v_mul_f32_e32 v5, v13, v13
	v_fmac_f32_e32 v4, v10, v10
	v_fmac_f32_e32 v5, v12, v12
	v_add_f32_e32 v4, v4, v5
	v_add_f32_e32 v2, v2, v4
	v_mul_f32_e32 v4, v7, v7
	v_mul_f32_e32 v5, v9, v9
	v_fmac_f32_e32 v4, v6, v6
	v_fmac_f32_e32 v5, v8, v8
	v_add_f32_e32 v4, v4, v5
	v_add_f32_e32 v2, v2, v4
	s_nop 1
	v_add_f32_dpp v2, v2, v2 quad_perm:[1,0,3,2] row_mask:0xf bank_mask:0xf
	s_nop 1
	v_add_f32_dpp v2, v2, v2 quad_perm:[2,3,0,1] row_mask:0xf bank_mask:0xf
	v_cvt_pk_bf16_f32 v4, v18, v19
	v_cvt_pk_bf16_f32 v5, v20, v21
	v_add_co_u32_e32 v18, vcc, 0x5901000, v60
	s_nop 1
	v_add_f32_dpp v2, v2, v2 row_half_mirror row_mask:0xf bank_mask:0xf
	v_addc_co_u32_e32 v19, vcc, 0, v61, vcc
	global_store_dwordx2 v[18:19], v[4:5], off offset:2048
	v_cvt_pk_bf16_f32 v4, v14, v15
	s_nop 1
	v_add_f32_dpp v2, v2, v2 row_mirror row_mask:0xf bank_mask:0xf
	v_cvt_pk_bf16_f32 v5, v16, v17
	global_store_dwordx2 v[18:19], v[4:5], off offset:2560
	v_cvt_pk_bf16_f32 v10, v10, v11
	v_cvt_pk_bf16_f32 v11, v12, v13
	v_mov_b32_e32 v14, v2
	v_mov_b32_e32 v100, v2
	s_nop 1
	v_permlane16_swap_b32 v14, v100
	v_add_f32_e32 v2, v14, v100
	v_mov_b32_e32 v4, v2
	v_mov_b32_e32 v100, v2
	s_nop 1
	v_permlane32_swap_b32 v100, v4
	global_store_dwordx2 v[18:19], v[10:11], off offset:3072
	v_cvt_pk_bf16_f32 v6, v6, v7
	v_cvt_pk_bf16_f32 v7, v8, v9
	global_store_dwordx2 v[18:19], v[6:7], off offset:3584
	s_and_saveexec_b64 s[42:43], s[6:7]
	s_cbranch_execz .LBB0_75
	v_add_f32_e32 v2, v2, v4
	v_add_co_u32_e32 v6, vcc, 0x10900000, v62
	v_cndmask_b32_e64 v2, 0, v2, s[4:5]
	s_nop 0
	v_addc_co_u32_e32 v7, vcc, 0, v63, vcc
	v_mov_b32_e32 v4, v3
	v_mov_b32_e32 v5, v3
	global_store_dwordx4 v[6:7], v[2:5], off offset:384
	s_branch .LBB0_75
